# attention: the wave on the P.V side of a step (the critical one of each SIMD pair) runs its MFMA/exp block at s_setprio 2
# speedup vs baseline: 1.0113x; 1.0108x over previous
.LBB0_254:
	s_and_b64 vcc, exec, s[20:21]
	s_barrier
	s_min_u32 s17, s4, 3
	s_lshl_b32 s17, s17, 6
	s_sub_i32 s17, s65, s17
	s_add_i32 s17, s15, s17
	s_mul_i32 s18, s14, 0x4400
	s_mul_i32 s19, s14, 0x5000
	s_add_i32 s40, s17, 0x1fc0
	v_add_u32_e32 v168, s18, v146
	v_add_u32_e32 v169, s19, v148
	s_lshl_b64 s[18:19], s[40:41], 9
	s_add_i32 s40, s17, 0x1fe0
	s_waitcnt vmcnt(3)
	ds_write_b128 v168, v[128:131]
	s_waitcnt vmcnt(2)
	ds_write_b128 v169, v[124:127] offset:52224
	s_waitcnt vmcnt(1)
	ds_write_b128 v168, v[132:135] offset:8704
	s_waitcnt vmcnt(0)
	ds_write_b128 v169, v[136:139] offset:62464
	v_lshl_add_u64 v[170:171], v[158:159], 0, s[18:19]
	s_lshl_b64 s[18:19], s[40:41], 9
	global_load_dwordx4 v[128:131], v[170:171], off
	global_load_dwordx4 v[124:127], v[170:171], off offset:256
	v_lshl_add_u64 v[170:171], v[158:159], 0, s[18:19]
	global_load_dwordx4 v[132:135], v[170:171], off
	global_load_dwordx4 v[136:139], v[170:171], off offset:256
	s_add_i32 s17, s12, 0xfffe4404
	s_and_b32 s17, s17, 4
	s_xor_b32 s40, s17, 4
	s_and_saveexec_b64 s[20:21], s[6:7]
	s_lshl_b32 s18, s40, 2
	s_add_i32 s18, s77, s18
	v_mov_b32_e32 v168, s18
	ds_write_b32 v168, v164
	s_or_b64 exec, exec, s[20:21]
	s_cbranch_vccnz .LBB0_256
	s_setprio 2
	s_mul_i32 s17, s16, 0x5000
	v_add3_u32 v166, v192, s17, v189
	v_add_u32_e32 v167, 0xcc00, v166
	s_waitcnt lgkmcnt(2)
	ds_read_b64_tr_b16 v[246:247], v166 offset:52224
	ds_read_b64_tr_b16 v[248:249], v166 offset:53504
	ds_read_b64_tr_b16 v[250:251], v166 offset:52288
	ds_read_b64_tr_b16 v[252:253], v166 offset:53568
	ds_read_b64_tr_b16 v[200:201], v166 offset:52352
	ds_read_b64_tr_b16 v[202:203], v166 offset:53632
	ds_read_b64_tr_b16 v[204:205], v166 offset:52416
	ds_read_b64_tr_b16 v[206:207], v166 offset:53696
	ds_read_b64_tr_b16 v[100:101], v166 offset:57344
	ds_read_b64_tr_b16 v[102:103], v166 offset:58624
	ds_read_b64_tr_b16 v[104:105], v166 offset:57408
	ds_read_b64_tr_b16 v[106:107], v166 offset:58688
	v_sub_f32_e32 v88, v88, v162
	v_sub_f32_e32 v89, v89, v162
	v_sub_f32_e32 v90, v90, v162
	v_sub_f32_e32 v91, v91, v162
	v_sub_f32_e32 v92, v92, v162
	v_sub_f32_e32 v93, v93, v162
	v_sub_f32_e32 v94, v94, v162
	v_sub_f32_e32 v95, v95, v162
	s_waitcnt lgkmcnt(10)
	v_mfma_f32_32x32x16_bf16 v[48:63], v[246:249], v[80:83], v[48:63]
	v_exp_f32_e32 v88, v88
	v_exp_f32_e32 v89, v89
	v_exp_f32_e32 v90, v90
	v_exp_f32_e32 v91, v91
	v_exp_f32_e32 v92, v92
	v_exp_f32_e32 v93, v93
	v_exp_f32_e32 v94, v94
	ds_read_b64_tr_b16 v[246:247], v166 offset:57472
	ds_read_b64_tr_b16 v[248:249], v166 offset:58752
	s_waitcnt lgkmcnt(10)
	v_mfma_f32_32x32x16_bf16 v[32:47], v[250:253], v[80:83], v[32:47]
	v_exp_f32_e32 v95, v95
	v_add_f32_e32 v153, v153, v88
	v_add_f32_e32 v153, v153, v89
	v_add_f32_e32 v153, v153, v90
	v_add_f32_e32 v153, v153, v91
	v_add_f32_e32 v153, v153, v92
	ds_read_b64_tr_b16 v[250:251], v166 offset:57536
	ds_read_b64_tr_b16 v[252:253], v166 offset:58816
	s_waitcnt lgkmcnt(10)
	v_mfma_f32_32x32x16_bf16 v[16:31], v[200:203], v[80:83], v[16:31]
	v_add_f32_e32 v153, v153, v93
	v_add_f32_e32 v153, v153, v94
	v_add_f32_e32 v153, v153, v95
	v_cvt_pk_bf16_f32 v88, v88, v89
	v_cvt_pk_bf16_f32 v89, v90, v91
	v_cvt_pk_bf16_f32 v90, v92, v93
	ds_read_b64_tr_b16 v[200:201], v166 offset:62464
	ds_read_b64_tr_b16 v[202:203], v166 offset:63744
	s_waitcnt lgkmcnt(10)
	v_mfma_f32_32x32x16_bf16 v[0:15], v[204:207], v[80:83], v[0:15]
	v_cvt_pk_bf16_f32 v91, v94, v95
	v_sub_f32_e32 v64, v64, v162
	v_sub_f32_e32 v65, v65, v162
	v_sub_f32_e32 v66, v66, v162
	v_sub_f32_e32 v67, v67, v162
	v_sub_f32_e32 v68, v68, v162
	v_sub_f32_e32 v69, v69, v162
	ds_read_b64_tr_b16 v[204:205], v166 offset:62528
	ds_read_b64_tr_b16 v[206:207], v166 offset:63808
	s_waitcnt lgkmcnt(10)
	v_mfma_f32_32x32x16_bf16 v[48:63], v[100:103], v[88:91], v[48:63]
	v_sub_f32_e32 v70, v70, v162
	v_sub_f32_e32 v71, v71, v162
	v_exp_f32_e32 v64, v64
	v_exp_f32_e32 v65, v65
	v_exp_f32_e32 v66, v66
	v_exp_f32_e32 v67, v67
	ds_read_b64_tr_b16 v[100:101], v166 offset:62592
	ds_read_b64_tr_b16 v[102:103], v166 offset:63872
	s_waitcnt lgkmcnt(10)
	v_mfma_f32_32x32x16_bf16 v[32:47], v[104:107], v[88:91], v[32:47]
	v_exp_f32_e32 v68, v68
	v_exp_f32_e32 v69, v69
	v_exp_f32_e32 v70, v70
	v_exp_f32_e32 v71, v71
	v_add_f32_e32 v153, v153, v64
	v_add_f32_e32 v153, v153, v65
	ds_read_b64_tr_b16 v[104:105], v166 offset:62656
	ds_read_b64_tr_b16 v[106:107], v166 offset:63936
	s_waitcnt lgkmcnt(10)
	v_mfma_f32_32x32x16_bf16 v[16:31], v[246:249], v[88:91], v[16:31]
	v_add_f32_e32 v153, v153, v66
	v_add_f32_e32 v153, v153, v67
	v_add_f32_e32 v153, v153, v68
	v_add_f32_e32 v153, v153, v69
	v_add_f32_e32 v153, v153, v70
	v_add_f32_e32 v153, v153, v71
	v_cvt_pk_bf16_f32 v64, v64, v65
	ds_read_b64_tr_b16 v[246:247], v167 offset:15360
	ds_read_b64_tr_b16 v[248:249], v167 offset:16640
	s_waitcnt lgkmcnt(10)
	v_mfma_f32_32x32x16_bf16 v[0:15], v[250:253], v[88:91], v[0:15]
	v_cvt_pk_bf16_f32 v65, v66, v67
	v_cvt_pk_bf16_f32 v66, v68, v69
	v_cvt_pk_bf16_f32 v67, v70, v71
	v_sub_f32_e32 v72, v72, v162
	v_sub_f32_e32 v73, v73, v162
	v_sub_f32_e32 v74, v74, v162
	ds_read_b64_tr_b16 v[250:251], v167 offset:15424
	ds_read_b64_tr_b16 v[252:253], v167 offset:16704
	s_waitcnt lgkmcnt(10)
	v_mfma_f32_32x32x16_bf16 v[48:63], v[200:203], v[64:67], v[48:63]
	v_sub_f32_e32 v75, v75, v162
	v_sub_f32_e32 v76, v76, v162
	v_sub_f32_e32 v77, v77, v162
	v_sub_f32_e32 v78, v78, v162
	v_sub_f32_e32 v79, v79, v162
	v_exp_f32_e32 v72, v72
	ds_read_b64_tr_b16 v[200:201], v167 offset:15488
	ds_read_b64_tr_b16 v[202:203], v167 offset:16768
	s_waitcnt lgkmcnt(10)
	v_mfma_f32_32x32x16_bf16 v[32:47], v[204:207], v[64:67], v[32:47]
	v_exp_f32_e32 v73, v73
	v_exp_f32_e32 v74, v74
	v_exp_f32_e32 v75, v75
	v_exp_f32_e32 v76, v76
	v_exp_f32_e32 v77, v77
	v_exp_f32_e32 v78, v78
	v_exp_f32_e32 v79, v79
	ds_read_b64_tr_b16 v[204:205], v167 offset:15552
	ds_read_b64_tr_b16 v[206:207], v167 offset:16832
	s_waitcnt lgkmcnt(10)
	v_mfma_f32_32x32x16_bf16 v[16:31], v[100:103], v[64:67], v[16:31]
	v_add_f32_e32 v153, v153, v72
	v_add_f32_e32 v153, v153, v73
	v_add_f32_e32 v153, v153, v74
	v_add_f32_e32 v153, v153, v75
	v_add_f32_e32 v153, v153, v76
	v_add_f32_e32 v153, v153, v77
	s_waitcnt lgkmcnt(8)
	v_mfma_f32_32x32x16_bf16 v[0:15], v[104:107], v[64:67], v[0:15]
	v_add_f32_e32 v153, v153, v78
	v_add_f32_e32 v153, v153, v79
	v_cvt_pk_bf16_f32 v72, v72, v73
	v_cvt_pk_bf16_f32 v73, v74, v75
	v_cvt_pk_bf16_f32 v74, v76, v77
	v_cvt_pk_bf16_f32 v75, v78, v79
	s_nop 0
	s_waitcnt lgkmcnt(6)
	v_mfma_f32_32x32x16_bf16 v[48:63], v[246:249], v[72:75], v[48:63]
	s_waitcnt lgkmcnt(4)
	v_mfma_f32_32x32x16_bf16 v[32:47], v[250:253], v[72:75], v[32:47]
	s_waitcnt lgkmcnt(2)
	v_mfma_f32_32x32x16_bf16 v[16:31], v[200:203], v[72:75], v[16:31]
	s_waitcnt lgkmcnt(0)
	v_mfma_f32_32x32x16_bf16 v[0:15], v[204:207], v[72:75], v[0:15]
.LBB0_256:
	s_setprio 0
	s_add_i32 s17, s78, s12
	s_add_i32 s17, s17, -4
	v_mov_b32_e32 v211, s17
	ds_read_b32 v210, v211
	s_add_i32 s17, s16, 1
	s_cmp_lg_u32 s16, 2
	s_cselect_b32 s17, s17, 0
	s_mul_i32 s17, s17, 0x4400
	v_add_u32_e32 v178, s17, v193
	ds_read_b128 v[246:249], v178
	ds_read_b128 v[250:253], v178 offset:32
	ds_read_b128 v[200:203], v178 offset:64
	ds_read_b128 v[204:207], v178 offset:96
	ds_read_b128 v[100:103], v178 offset:8704
	ds_read_b128 v[104:107], v178 offset:8736
	s_add_i32 s17, s12, 0xfffe4404
	s_and_b32 s17, s17, 4
	s_xor_b32 s40, s17, 4
	s_lshl_b32 s18, s40, 2
	s_add_i32 s18, s18, 0x1c040
	v_mov_b32_e32 v176, s18
	s_lshl_b32 s17, s17, 2
	s_add_i32 s17, s17, 0x1c060
	v_mov_b32_e32 v177, s17
	s_waitcnt lgkmcnt(7)
	s_barrier
	ds_read_b128 v[168:171], v176
	ds_read_b128 v[172:175], v177
	s_waitcnt lgkmcnt(7)
	v_mfma_f32_32x32x16_bf16 v[80:95], v[246:249], v[108:111], v[214:229]
	ds_read_b128 v[246:249], v178 offset:8768
	s_waitcnt lgkmcnt(7)
	v_mfma_f32_32x32x16_bf16 v[80:95], v[250:253], v[112:115], v[80:95]
	ds_read_b128 v[250:253], v178 offset:8800
	s_waitcnt lgkmcnt(7)
	v_mfma_f32_32x32x16_bf16 v[80:95], v[200:203], v[116:119], v[80:95]
	s_waitcnt lgkmcnt(6)
	v_mfma_f32_32x32x16_bf16 v[80:95], v[204:207], v[120:123], v[80:95]
	s_waitcnt lgkmcnt(5)
	v_mfma_f32_32x32x16_bf16 v[64:79], v[100:103], v[108:111], v[230:245]
	s_waitcnt lgkmcnt(4)
	v_mfma_f32_32x32x16_bf16 v[64:79], v[104:107], v[112:115], v[64:79]
	s_waitcnt lgkmcnt(1)
	v_mfma_f32_32x32x16_bf16 v[64:79], v[246:249], v[116:119], v[64:79]
	s_waitcnt lgkmcnt(0)
	v_mfma_f32_32x32x16_bf16 v[64:79], v[250:253], v[120:123], v[64:79]
	s_waitcnt lgkmcnt(0)
	v_and_b32_e32 v168, v168, v169
	v_and_b32_e32 v168, v168, v170
	v_and_b32_e32 v168, v168, v171
	v_and_b32_e32 v168, v168, v172
	v_and_b32_e32 v168, v168, v173
	v_and_b32_e32 v168, v168, v174
	v_and_b32_e32 v168, v168, v175
	v_cmp_ne_u32_e32 vcc, 0, v168
	s_cbranch_vccz .LBB0_260
	s_branch .LBB0_262
